# diff-attn: softmax scale folded into shared-K weights at PREP, running max folded into QK MFMA C operand, exp2 directly off accumulator (no per-element fma) on v_m11
# speedup vs baseline: 1.0071x; 1.0017x over previous
.LBB0_44:
	s_cmpk_gt_i32 s54, 0x7ff
	s_cbranch_scc1 .LBB0_43
	s_waitcnt vmcnt(10)
	v_mov_b32_e32 v54, v224
	s_ashr_i32 s55, s54, 5
	v_readfirstlane_b32 s0, v54
	s_sub_i32 s57, 63, s55
	s_ashr_i32 s0, s0, 1
	s_lshl_b32 s1, s57, 7
	s_and_b32 s52, s0, 0xffffffe0
	s_add_i32 s52, s52, s1
	s_bfe_u32 s56, s54, 0x10004
	s_and_b32 s48, s54, 15
	v_and_or_b32 v170, v54, 15, s52
	s_lshl_b32 s94, s56, 13
	s_lshl_b32 s0, s48, 7
	v_ashrrev_i32_e32 v171, 31, v170
	s_add_u32 s0, s13, s0
	v_lshl_add_u64 v[172:173], v[170:171], 0, s[94:95]
	s_addc_u32 s1, s14, 0
	v_and_b32_e32 v0, 16, v54
	v_lshlrev_b64 v[2:3], 11, v[172:173]
	v_cmp_eq_u32_e64 s[40:41], 0, v0
	s_waitcnt vmcnt(1)
	v_lshl_add_u64 v[14:15], s[0:1], 0, v[2:3]
	v_and_b32_e32 v0, 48, v54
	v_lshl_add_u64 v[6:7], v[14:15], 0, v[0:1]
	v_lshlrev_b64 v[10:11], 6, v[170:171]
	global_load_dwordx4 v[2:5], v[6:7], off offset:64
	s_nop 0
	global_load_dwordx4 v[6:9], v[6:7], off
	v_lshl_add_u64 v[22:23], s[4:5], 0, v[10:11]
	global_load_dwordx4 v[10:13], v[14:15], off
	s_nop 0
	global_load_dwordx4 v[14:17], v[14:15], off offset:16
	v_or_b32_e32 v176, 16, v170
	v_and_b32_e32 v55, 63, v54
	v_ashrrev_i32_e32 v177, 31, v176
	v_cmp_gt_u32_e32 vcc, 32, v55
	v_lshl_add_u64 v[174:175], v[176:177], 0, s[94:95]
	v_mov_b32_e32 v90, v1
	v_mov_b32_e32 v91, v1
	v_mov_b32_e32 v92, v1
	v_mov_b32_e32 v93, v1
	v_lshlrev_b32_e32 v193, 4, v54
	v_lshlrev_b32_e32 v197, 4, v55
	v_mov_b64_e32 v[70:71], v[90:91]
	v_mov_b64_e32 v[104:105], v[92:93]
	v_mov_b64_e32 v[66:67], v[90:91]
	v_mov_b64_e32 v[100:101], v[92:93]
	v_mov_b64_e32 v[58:59], v[90:91]
	v_mov_b64_e32 v[96:97], v[92:93]
	v_mov_b64_e32 v[86:87], v[90:91]
	v_mov_b64_e32 v[82:83], v[90:91]
	v_mov_b64_e32 v[78:79], v[90:91]
	v_mov_b64_e32 v[74:75], v[90:91]
	s_mov_b32 s49, 63
	s_mov_b32 s53, 0
	v_mov_b32_e32 v200, 0
	v_mov_b32_e32 v198, 0
	v_mov_b64_e32 v[72:73], v[92:93]
	v_mov_b64_e32 v[102:103], v[90:91]
	v_mov_b64_e32 v[68:69], v[92:93]
	v_mov_b64_e32 v[98:99], v[90:91]
	v_mov_b64_e32 v[60:61], v[92:93]
	v_mov_b64_e32 v[94:95], v[90:91]
	v_mov_b64_e32 v[88:89], v[92:93]
	v_mov_b64_e32 v[84:85], v[92:93]
	v_mov_b64_e32 v[80:81], v[92:93]
	v_mov_b64_e32 v[76:77], v[92:93]
	s_waitcnt vmcnt(1)
	v_lshlrev_b32_e32 v26, 16, v10
	s_waitcnt vmcnt(0)
	v_lshlrev_b32_e32 v27, 16, v14
	v_and_b32_e32 v29, 0xffff0000, v14
	v_and_b32_e32 v28, 0xffff0000, v10
	v_lshlrev_b32_e32 v31, 16, v15
	v_lshlrev_b32_e32 v30, 16, v11
	v_and_b32_e32 v33, 0xffff0000, v15
	v_and_b32_e32 v32, 0xffff0000, v11
	v_lshlrev_b32_e32 v35, 16, v16
	v_lshlrev_b32_e32 v34, 16, v12
	v_and_b32_e32 v37, 0xffff0000, v16
	v_and_b32_e32 v36, 0xffff0000, v12
	v_lshlrev_b32_e32 v39, 16, v17
	v_lshlrev_b32_e32 v38, 16, v13
	v_and_b32_e32 v41, 0xffff0000, v17
	v_and_b32_e32 v40, 0xffff0000, v13
	global_load_dwordx4 v[10:13], v[22:23], off offset:48
	global_load_dwordx4 v[14:17], v[22:23], off offset:16
	global_load_dwordx4 v[18:21], v[22:23], off offset:32
	s_nop 0
	global_load_dwordx4 v[22:25], v[22:23], off
	s_waitcnt vmcnt(1)
	v_mov_b32_e32 v43, v18
	s_waitcnt vmcnt(0)
	v_mov_b32_e32 v42, v22
	v_pk_mul_f32 v[42:43], v[42:43], v[26:27]
	s_nop 0
	v_sub_f32_e32 v44, v42, v43
	v_mov_b32_e32 v42, v18
	v_mov_b32_e32 v43, v22
	v_pk_mul_f32 v[26:27], v[42:43], v[26:27]
	v_mov_b32_e32 v22, v19
	v_add_f32_e32 v18, v26, v27
	v_cndmask_b32_e64 v42, v18, v44, s[40:41]
	v_mov_b32_e32 v18, v23
	v_pk_mul_f32 v[26:27], v[18:19], v[28:29]
	v_pk_mul_f32 v[18:19], v[22:23], v[28:29]
	v_sub_f32_e32 v26, v26, v27
	v_add_f32_e32 v18, v19, v18
	v_cndmask_b32_e64 v22, v18, v26, s[40:41]
	v_mov_b32_e32 v18, v24
	v_mov_b32_e32 v19, v20
	v_pk_mul_f32 v[18:19], v[18:19], v[30:31]
	s_nop 0
	v_sub_f32_e32 v23, v18, v19
	v_mov_b32_e32 v18, v20
	v_mov_b32_e32 v19, v24
	v_pk_mul_f32 v[18:19], v[18:19], v[30:31]
	v_mov_b32_e32 v20, v25
	v_add_f32_e32 v18, v19, v18
	v_cndmask_b32_e64 v23, v18, v23, s[40:41]
	v_pk_mul_f32 v[18:19], v[20:21], v[32:33]
	v_mov_b32_e32 v24, v21
	v_sub_f32_e32 v20, v18, v19
	v_pk_mul_f32 v[18:19], v[24:25], v[32:33]
	s_nop 0
	v_add_f32_e32 v18, v19, v18
	v_cndmask_b32_e64 v20, v18, v20, s[40:41]
	v_mov_b32_e32 v18, v14
	v_mov_b32_e32 v19, v10
	v_pk_mul_f32 v[18:19], v[18:19], v[34:35]
	s_nop 0
	v_sub_f32_e32 v21, v18, v19
	v_mov_b32_e32 v18, v10
	v_mov_b32_e32 v19, v14
	v_pk_mul_f32 v[18:19], v[18:19], v[34:35]
	v_mov_b32_e32 v14, v11
	v_add_f32_e32 v10, v19, v18
	v_cndmask_b32_e64 v21, v10, v21, s[40:41]
	v_mov_b32_e32 v10, v15
	v_pk_mul_f32 v[18:19], v[10:11], v[36:37]
	v_pk_mul_f32 v[10:11], v[14:15], v[36:37]
	v_sub_f32_e32 v18, v18, v19
	v_add_f32_e32 v10, v11, v10
	v_cndmask_b32_e64 v14, v10, v18, s[40:41]
	v_mov_b32_e32 v10, v16
	v_mov_b32_e32 v11, v12
	v_pk_mul_f32 v[10:11], v[10:11], v[38:39]
	v_lshlrev_b64 v[18:19], 6, v[176:177]
	v_sub_f32_e32 v15, v10, v11
	v_mov_b32_e32 v10, v12
	v_mov_b32_e32 v11, v16
	v_pk_mul_f32 v[10:11], v[10:11], v[38:39]
	v_mov_b32_e32 v12, v17
	v_add_f32_e32 v10, v11, v10
	v_cndmask_b32_e64 v15, v10, v15, s[40:41]
	v_pk_mul_f32 v[10:11], v[12:13], v[40:41]
	v_mov_b32_e32 v16, v13
	v_sub_f32_e32 v12, v10, v11
	v_pk_mul_f32 v[10:11], v[16:17], v[40:41]
	v_cvt_pk_bf16_f32 v13, v21, v14
	v_add_f32_e32 v10, v11, v10
	v_cndmask_b32_e64 v10, v10, v12, s[40:41]
	v_cvt_pk_bf16_f32 v11, v42, v22
	v_cvt_pk_bf16_f32 v10, v15, v10
	v_cndmask_b32_e32 v9, v9, v10, vcc
	v_cndmask_b32_e32 v6, v6, v11, vcc
	v_lshlrev_b64 v[10:11], 11, v[174:175]
	v_cvt_pk_bf16_f32 v12, v23, v20
	v_lshl_add_u64 v[22:23], s[0:1], 0, v[10:11]
	v_lshl_add_u64 v[14:15], v[22:23], 0, v[0:1]
	v_cndmask_b32_e32 v8, v8, v13, vcc
	v_cndmask_b32_e32 v7, v7, v12, vcc
	global_load_dwordx4 v[10:13], v[14:15], off offset:64
	s_nop 0
	global_load_dwordx4 v[14:17], v[14:15], off
	v_lshl_add_u64 v[30:31], s[4:5], 0, v[18:19]
	global_load_dwordx4 v[18:21], v[22:23], off
	s_nop 0
	global_load_dwordx4 v[22:25], v[22:23], off offset:16
	s_waitcnt vmcnt(1)
	v_lshlrev_b32_e32 v48, 16, v18
	s_waitcnt vmcnt(0)
	v_lshlrev_b32_e32 v49, 16, v22
	v_and_b32_e32 v47, 0xffff0000, v22
	v_and_b32_e32 v46, 0xffff0000, v18
	v_lshlrev_b32_e32 v45, 16, v23
	v_lshlrev_b32_e32 v44, 16, v19
	v_and_b32_e32 v43, 0xffff0000, v23
	v_and_b32_e32 v42, 0xffff0000, v19
	v_lshlrev_b32_e32 v41, 16, v24
	v_lshlrev_b32_e32 v40, 16, v20
	v_and_b32_e32 v39, 0xffff0000, v24
	v_and_b32_e32 v38, 0xffff0000, v20
	v_lshlrev_b32_e32 v37, 16, v25
	v_lshlrev_b32_e32 v36, 16, v21
	v_and_b32_e32 v35, 0xffff0000, v25
	v_and_b32_e32 v34, 0xffff0000, v21
	global_load_dwordx4 v[18:21], v[30:31], off offset:48
	global_load_dwordx4 v[22:25], v[30:31], off offset:16
	global_load_dwordx4 v[26:29], v[30:31], off offset:32
	s_nop 0
	global_load_dwordx4 v[30:33], v[30:31], off
	s_barrier
	s_waitcnt vmcnt(1)
	v_mov_b32_e32 v51, v26
	s_waitcnt vmcnt(0)
	v_mov_b32_e32 v50, v30
	v_pk_mul_f32 v[50:51], v[50:51], v[48:49]
	s_nop 0
	v_sub_f32_e32 v0, v50, v51
	v_mov_b32_e32 v50, v26
	v_mov_b32_e32 v51, v30
	v_pk_mul_f32 v[48:49], v[50:51], v[48:49]
	v_mov_b32_e32 v30, v27
	v_add_f32_e32 v26, v48, v49
	v_cndmask_b32_e64 v0, v26, v0, s[40:41]
	v_mov_b32_e32 v26, v31
	v_pk_mul_f32 v[48:49], v[26:27], v[46:47]
	v_pk_mul_f32 v[26:27], v[30:31], v[46:47]
	v_sub_f32_e32 v48, v48, v49
	v_add_f32_e32 v26, v27, v26
	v_cndmask_b32_e64 v30, v26, v48, s[40:41]
	v_mov_b32_e32 v26, v32
	v_mov_b32_e32 v27, v28
	v_pk_mul_f32 v[26:27], v[26:27], v[44:45]
	v_cvt_pk_bf16_f32 v0, v0, v30
	v_sub_f32_e32 v31, v26, v27
	v_mov_b32_e32 v26, v28
	v_mov_b32_e32 v27, v32
	v_pk_mul_f32 v[26:27], v[26:27], v[44:45]
	v_mov_b32_e32 v28, v33
	v_add_f32_e32 v26, v27, v26
	v_cndmask_b32_e64 v31, v26, v31, s[40:41]
	v_pk_mul_f32 v[26:27], v[28:29], v[42:43]
	v_mov_b32_e32 v32, v29
	v_sub_f32_e32 v28, v26, v27
	v_pk_mul_f32 v[26:27], v[32:33], v[42:43]
	v_cndmask_b32_e32 v14, v14, v0, vcc
	v_add_f32_e32 v26, v27, v26
	v_cndmask_b32_e64 v28, v26, v28, s[40:41]
	v_mov_b32_e32 v26, v22
	v_mov_b32_e32 v27, v18
	v_pk_mul_f32 v[26:27], v[26:27], v[40:41]
	v_mov_b64_e32 v[46:47], v[90:91]
	v_sub_f32_e32 v29, v26, v27
	v_mov_b32_e32 v26, v18
	v_mov_b32_e32 v27, v22
	v_pk_mul_f32 v[26:27], v[26:27], v[40:41]
	v_mov_b32_e32 v22, v19
	v_add_f32_e32 v18, v27, v26
	v_cndmask_b32_e64 v29, v18, v29, s[40:41]
	v_mov_b32_e32 v18, v23
	v_pk_mul_f32 v[26:27], v[18:19], v[38:39]
	v_pk_mul_f32 v[18:19], v[22:23], v[38:39]
	v_sub_f32_e32 v26, v26, v27
	v_add_f32_e32 v18, v19, v18
	v_cndmask_b32_e64 v22, v18, v26, s[40:41]
	v_mov_b32_e32 v18, v24
	v_mov_b32_e32 v19, v20
	v_pk_mul_f32 v[18:19], v[18:19], v[36:37]
	v_lshlrev_b32_e32 v26, 3, v54
	v_sub_f32_e32 v23, v18, v19
	v_mov_b32_e32 v18, v20
	v_mov_b32_e32 v19, v24
	v_pk_mul_f32 v[18:19], v[18:19], v[36:37]
	v_mov_b32_e32 v20, v25
	v_add_f32_e32 v18, v19, v18
	v_cndmask_b32_e64 v23, v18, v23, s[40:41]
	v_pk_mul_f32 v[18:19], v[20:21], v[34:35]
	v_mov_b32_e32 v24, v21
	v_sub_f32_e32 v20, v18, v19
	v_pk_mul_f32 v[18:19], v[24:25], v[34:35]
	v_ashrrev_i32_e32 v27, 31, v26
	v_add_f32_e32 v18, v19, v18
	v_cndmask_b32_e64 v18, v18, v20, s[40:41]
	s_lshl_b32 s40, s54, 20
	v_cvt_pk_bf16_f32 v20, v29, v22
	s_and_b32 s0, s40, 0x1f00000
	v_add_u32_e32 v22, 0x800, v26
	v_cvt_pk_bf16_f32 v18, v23, v18
	s_add_u32 s0, s15, s0
	v_ashrrev_i32_e32 v23, 31, v22
	v_cvt_pk_bf16_f32 v19, v31, v28
	s_addc_u32 s1, s44, 0
	v_lshlrev_b64 v[28:29], 1, v[26:27]
	v_lshlrev_b64 v[34:35], 1, v[22:23]
	v_cndmask_b32_e32 v17, v17, v18, vcc
	v_cndmask_b32_e32 v15, v15, v19, vcc
	v_lshl_add_u64 v[18:19], s[0:1], 0, v[28:29]
	v_lshl_add_u64 v[22:23], s[0:1], 0, v[34:35]
	s_and_b32 s0, s40, 0xe00000
	s_lshl_b32 s1, s56, 24
	s_lshl_b32 s41, s57, 1
	s_or_b32 s40, s1, s0
	s_add_u32 s0, s45, s40
	s_addc_u32 s1, s46, 0
	v_lshl_add_u64 v[30:31], s[0:1], 0, v[28:29]
	v_lshl_add_u64 v[36:37], s[0:1], 0, v[34:35]
	global_load_dwordx4 v[30:33], v[30:31], off
	v_cndmask_b32_e32 v16, v16, v20, vcc
	global_load_dwordx4 v[42:45], v[36:37], off
	v_add_u32_e32 v36, 0x1000, v26
	v_ashrrev_i32_e32 v37, 31, v36
	v_add_u32_e32 v26, 0x1800, v26
	v_lshlrev_b64 v[36:37], 1, v[36:37]
	v_ashrrev_i32_e32 v27, 31, v26
	v_lshl_add_u64 v[38:39], s[0:1], 0, v[36:37]
	v_lshlrev_b64 v[26:27], 1, v[26:27]
	global_load_dwordx4 v[50:53], v[38:39], off
	v_lshl_add_u64 v[38:39], s[0:1], 0, v[26:27]
	global_load_dwordx4 v[18:21], v[18:19], off
	s_add_i32 s0, s41, 2
	global_load_dwordx4 v[22:25], v[22:23], off
	v_readlane_b32 s1, v254, 13
	global_load_dwordx4 v[62:65], v[38:39], off
	s_add_u32 s40, s1, s40
	v_readlane_b32 s1, v254, 14
	v_cmp_lt_i32_e32 vcc, v247, v214
	s_addc_u32 s41, s1, 0
	s_and_b32 s1, s54, 31
	v_cndmask_b32_e32 v0, v225, v247, vcc
	v_cmp_lt_i32_e32 vcc, v246, v214
	v_mov_b32_e32 v180, v34
	v_mov_b32_e32 v181, v28
	v_mov_b32_e32 v182, v36
	s_mov_b64 s[98:99], s[40:41]
	v_mov_b32_e32 v184, v26
	s_lshl_b32 s1, s1, 20
	v_readlane_b32 s40, v254, 15
	v_lshlrev_b32_e32 v177, 2, v0
	v_cndmask_b32_e32 v0, v225, v246, vcc
	s_add_u32 s40, s40, s1
	v_readlane_b32 s1, v254, 16
	v_lshlrev_b32_e32 v171, 2, v0
	v_lshrrev_b32_e32 v0, 2, v54
	s_addc_u32 s41, s1, 0
	v_and_b32_e32 v192, 12, v0
	s_mov_b64 s[2:3], s[40:41]
	s_lshl_b32 s1, s55, 1
	v_mov_b32_e32 v0, v1
	v_mov_b64_e32 v[54:55], v[90:91]
	v_mov_b64_e32 v[38:39], v[90:91]
	v_mov_b64_e32 v[34:35], v[90:91]
	v_mov_b64_e32 v[26:27], v[90:91]
	s_sub_i32 s1, 0, s1
	s_movk_i32 s54, 0xff80
	v_mov_b64_e32 v[56:57], v[92:93]
	v_mov_b64_e32 v[48:49], v[92:93]
	v_mov_b64_e32 v[40:41], v[92:93]
	v_mov_b64_e32 v[36:37], v[92:93]
	v_mov_b64_e32 v[28:29], v[92:93]
	v_mov_b64_e32 v[178:179], v[0:1]
	s_waitcnt vmcnt(0)
	ds_write_b128 v193, v[18:21]
	ds_write_b128 v193, v[22:25] offset:4096
	ds_write_b128 v193, v[30:33] offset:8192
	ds_write_b128 v193, v[42:45] offset:12288
	ds_write_b128 v193, v[50:53] offset:16384
	ds_write_b128 v193, v[62:65] offset:20480
	v_mov_b32_e32 v18, 0
	v_mov_b32_e32 v19, 0
	v_mov_b32_e32 v20, 0
	v_mov_b32_e32 v21, 0
	v_mov_b32_e32 v22, 0
	v_mov_b32_e32 v23, 0
	v_mov_b32_e32 v24, 0
	v_mov_b32_e32 v25, 0

.LBB0_48:
	v_add_u32_e32 v0, s40, v197
	ds_read_b128 v[106:109], v0
	ds_read_b128 v[110:113], v0 offset:1024
	ds_read_b128 v[114:117], v0 offset:2048
	ds_read_b128 v[118:121], v0 offset:3072
	ds_read_b128 v[122:125], v0 offset:4096
	ds_read_b128 v[126:129], v0 offset:5120
	ds_read_b128 v[130:133], v0 offset:6144
	ds_read_b128 v[134:137], v0 offset:7168
	s_waitcnt lgkmcnt(7)
	v_mfma_f32_16x16x32_bf16 v[138:141], v[106:109], v[6:9], v[18:21]
	v_mfma_f32_16x16x32_bf16 v[106:109], v[106:109], v[14:17], v[22:25]
	s_waitcnt lgkmcnt(6)
	v_mfma_f32_16x16x32_bf16 v[166:169], v[110:113], v[2:5], v[138:141]
	v_mfma_f32_16x16x32_bf16 v[150:153], v[110:113], v[10:13], v[106:109]
	s_waitcnt lgkmcnt(5)
	v_mfma_f32_16x16x32_bf16 v[106:109], v[114:117], v[6:9], v[18:21]
	v_mfma_f32_16x16x32_bf16 v[110:113], v[114:117], v[14:17], v[22:25]
	s_waitcnt lgkmcnt(4)
	v_mfma_f32_16x16x32_bf16 v[162:165], v[118:121], v[2:5], v[106:109]
	v_mfma_f32_16x16x32_bf16 v[146:149], v[118:121], v[10:13], v[110:113]
	s_waitcnt lgkmcnt(3)
	v_mfma_f32_16x16x32_bf16 v[106:109], v[122:125], v[6:9], v[18:21]
	v_mfma_f32_16x16x32_bf16 v[110:113], v[122:125], v[14:17], v[22:25]
	s_waitcnt lgkmcnt(2)
	v_mfma_f32_16x16x32_bf16 v[158:161], v[126:129], v[2:5], v[106:109]
	v_mfma_f32_16x16x32_bf16 v[142:145], v[126:129], v[10:13], v[110:113]
	s_waitcnt lgkmcnt(1)
	v_mfma_f32_16x16x32_bf16 v[106:109], v[130:133], v[6:9], v[18:21]
	v_mfma_f32_16x16x32_bf16 v[110:113], v[130:133], v[14:17], v[22:25]
	s_waitcnt lgkmcnt(0)
	v_mfma_f32_16x16x32_bf16 v[154:157], v[134:137], v[2:5], v[106:109]
	v_mfma_f32_16x16x32_bf16 v[138:141], v[134:137], v[10:13], v[110:113]
	ds_read_b128 v[134:137], v0 offset:8192
	ds_read_b128 v[130:133], v0 offset:9216
	ds_read_b128 v[126:129], v0 offset:10240
	ds_read_b128 v[122:125], v0 offset:11264
	ds_read_b128 v[118:121], v0 offset:12288
	ds_read_b128 v[114:117], v0 offset:13312
	ds_read_b128 v[110:113], v0 offset:14336
	ds_read_b128 v[106:109], v0 offset:15360
	s_cmp_le_i32 s49, s52
	s_cbranch_scc1 .LBB0_50
	v_add_u32_e32 v194, s49, v192
	v_subrev_u32_e32 v195, 63, v194
	v_cmp_lt_i32_e64 s[40:41], v195, v170
	v_subrev_u32_e32 v196, 61, v194
	v_subrev_u32_e32 v199, 60, v194
	v_cndmask_b32_e64 v167, v222, v167, s[40:41]
	v_cmp_le_i32_e64 s[40:41], v196, v170
	v_cmp_gt_i32_e32 vcc, v195, v170
	v_subrev_u32_e32 v201, 28, v194
	v_cndmask_b32_e64 v168, v222, v168, s[40:41]
	v_cmp_le_i32_e64 s[40:41], v199, v170
	v_cndmask_b32_e32 v166, v166, v222, vcc
	v_cndmask_b32_e32 v146, v146, v222, vcc
	v_cndmask_b32_e64 v169, v222, v169, s[40:41]
	v_cmp_le_i32_e64 s[40:41], v195, v176
	s_nop 1
	v_cndmask_b32_e64 v150, v222, v150, s[40:41]
	v_cmp_lt_i32_e64 s[40:41], v195, v176
	v_subrev_u32_e32 v195, 47, v194
	s_nop 0
	v_cndmask_b32_e64 v151, v222, v151, s[40:41]
	v_cmp_le_i32_e64 s[40:41], v196, v176
	v_subrev_u32_e32 v196, 45, v194
	s_nop 0
	v_cndmask_b32_e64 v152, v222, v152, s[40:41]
	v_cmp_le_i32_e64 s[40:41], v199, v176
	v_subrev_u32_e32 v199, 44, v194
	s_nop 0
	v_cndmask_b32_e64 v153, v222, v153, s[40:41]
	v_cmp_le_i32_e64 s[40:41], v195, v170
	v_subrev_u32_e32 v195, 46, v194
	v_cmp_le_i32_e32 vcc, v195, v176
	v_cndmask_b32_e64 v162, v222, v162, s[40:41]
	v_cmp_le_i32_e64 s[40:41], v195, v170
	v_cndmask_b32_e32 v147, v222, v147, vcc
	v_cmp_le_i32_e32 vcc, v196, v176
	v_subrev_u32_e32 v195, 31, v194
	v_cndmask_b32_e64 v163, v222, v163, s[40:41]
	v_cndmask_b32_e32 v148, v222, v148, vcc
	v_cmp_le_i32_e32 vcc, v199, v176
	v_cmp_le_i32_e64 s[40:41], v196, v170
	v_subrev_u32_e32 v196, 30, v194
	v_cndmask_b32_e32 v149, v222, v149, vcc
	v_cmp_le_i32_e32 vcc, v195, v170
	v_cndmask_b32_e64 v164, v222, v164, s[40:41]
	v_cmp_le_i32_e64 s[40:41], v199, v170
	v_cndmask_b32_e32 v158, v222, v158, vcc
	v_cmp_le_i32_e32 vcc, v196, v170
	v_subrev_u32_e32 v199, 29, v194
	v_cndmask_b32_e64 v165, v222, v165, s[40:41]
	v_cndmask_b32_e32 v159, v222, v159, vcc
	v_cmp_le_i32_e32 vcc, v199, v170
	s_nop 1
	v_cndmask_b32_e32 v160, v222, v160, vcc
	v_cmp_le_i32_e32 vcc, v201, v170
	s_nop 1
	v_cndmask_b32_e32 v161, v222, v161, vcc
	v_cmp_le_i32_e32 vcc, v195, v176
	v_add_u32_e32 v195, -15, v194
	s_nop 0
	v_cndmask_b32_e32 v142, v222, v142, vcc
	v_cmp_le_i32_e32 vcc, v196, v176
	v_add_u32_e32 v196, -14, v194
	s_nop 0
	v_cndmask_b32_e32 v143, v222, v143, vcc
	v_cmp_le_i32_e32 vcc, v199, v176
	v_add_u32_e32 v199, -13, v194
	v_add_u32_e32 v194, -12, v194
	v_cndmask_b32_e32 v144, v222, v144, vcc
	v_cmp_le_i32_e32 vcc, v201, v176
	s_nop 1
	v_cndmask_b32_e32 v145, v222, v145, vcc
	v_cmp_le_i32_e32 vcc, v195, v170
	s_nop 1
	v_cndmask_b32_e32 v154, v222, v154, vcc
	v_cmp_le_i32_e32 vcc, v196, v170
	s_nop 1
	v_cndmask_b32_e32 v155, v222, v155, vcc
	v_cmp_le_i32_e32 vcc, v199, v170
	s_nop 1
	v_cndmask_b32_e32 v156, v222, v156, vcc
	v_cmp_le_i32_e32 vcc, v194, v170
	s_nop 1
	v_cndmask_b32_e32 v157, v222, v157, vcc
	v_cmp_le_i32_e32 vcc, v195, v176
	s_nop 1
	v_cndmask_b32_e32 v138, v222, v138, vcc
	v_cmp_le_i32_e32 vcc, v196, v176
	s_nop 1
	v_cndmask_b32_e32 v139, v222, v139, vcc
	v_cmp_le_i32_e32 vcc, v199, v176
	s_nop 1
	v_cndmask_b32_e32 v140, v222, v140, vcc
	v_cmp_le_i32_e32 vcc, v194, v176
	s_nop 1
	v_cndmask_b32_e32 v141, v222, v141, vcc
.LBB0_50:
	v_max3_f32 v194, v166, v167, v168
	v_max3_f32 v195, v169, v162, v163
	v_max3_f32 v196, v164, v165, v158
	v_max3_f32 v194, v194, v159, v160
	v_max3_f32 v195, v195, v161, v154
	v_max3_f32 v196, v196, v155, v156
	v_max3_f32 v194, v194, v195, v157
	v_max_f32_e32 v194, v194, v196
	v_max3_f32 v195, v150, v151, v152
	v_max3_f32 v196, v153, v146, v147
	v_max3_f32 v199, v148, v149, v142
	v_max3_f32 v195, v195, v143, v144
	v_max3_f32 v196, v196, v145, v138
	v_max3_f32 v199, v199, v139, v140
	v_max3_f32 v195, v195, v196, v141
	v_max_f32_e32 v195, v195, v199
	v_mov_b32_e32 v196, v194
	v_mov_b32_e32 v199, v195
	s_nop 1
	v_permlane16_swap_b32_e32 v194, v196
	v_permlane16_swap_b32_e32 v195, v199
	v_max_f32_e32 v194, v194, v196
	v_max_f32_e32 v195, v195, v199
	v_mov_b32_e32 v196, v194
	v_mov_b32_e32 v199, v195
	s_nop 1
	v_permlane32_swap_b32_e32 v194, v196
	v_permlane32_swap_b32_e32 v195, v199
	v_max_f32_e32 v195, v195, v199
	v_max_f32_e32 v194, v194, v196
	s_cmpk_eq_i32 s54, 0xff80
	s_cbranch_scc1 .Lmy_first
	v_cmp_lt_f32_e32 vcc, 0, v194
	v_cmp_lt_f32_e64 s[40:41], 0, v195
	s_or_b64 vcc, vcc, s[40:41]
	s_cbranch_vccz .LBB0_52
	v_max_f32_e32 v199, 0, v194
	v_max_f32_e32 v201, 0, v195
	v_sub_f32_e32 v194, 0, v199
	v_exp_f32_e32 v194, v194
	s_nop 0
	v_pk_mul_f32 v[92:93], v[92:93], v[194:195] op_sel_hi:[1,0]
	v_pk_mul_f32 v[90:91], v[90:91], v[194:195] op_sel_hi:[1,0]
	v_pk_mul_f32 v[104:105], v[104:105], v[194:195] op_sel_hi:[1,0]
	v_pk_mul_f32 v[102:103], v[102:103], v[194:195] op_sel_hi:[1,0]
	v_pk_mul_f32 v[100:101], v[100:101], v[194:195] op_sel_hi:[1,0]
	v_pk_mul_f32 v[98:99], v[98:99], v[194:195] op_sel_hi:[1,0]
	v_pk_mul_f32 v[96:97], v[96:97], v[194:195] op_sel_hi:[1,0]
	v_pk_mul_f32 v[94:95], v[94:95], v[194:195] op_sel_hi:[1,0]
	v_pk_mul_f32 v[88:89], v[88:89], v[194:195] op_sel_hi:[1,0]
	v_pk_mul_f32 v[86:87], v[86:87], v[194:195] op_sel_hi:[1,0]
	v_pk_mul_f32 v[84:85], v[84:85], v[194:195] op_sel_hi:[1,0]
	v_pk_mul_f32 v[82:83], v[82:83], v[194:195] op_sel_hi:[1,0]
	v_pk_mul_f32 v[80:81], v[80:81], v[194:195] op_sel_hi:[1,0]
	v_pk_mul_f32 v[78:79], v[78:79], v[194:195] op_sel_hi:[1,0]
	v_pk_mul_f32 v[76:77], v[76:77], v[194:195] op_sel_hi:[1,0]
	v_pk_mul_f32 v[74:75], v[74:75], v[194:195] op_sel_hi:[1,0]
	v_sub_f32_e32 v195, 0, v201
	v_exp_f32_e32 v195, v195
	s_nop 0
	v_pk_mul_f32 v[178:179], v[178:179], v[194:195]
	v_mov_b32_e32 v194, v195
	v_pk_mul_f32 v[72:73], v[72:73], v[194:195] op_sel_hi:[1,0]
	v_pk_mul_f32 v[70:71], v[70:71], v[194:195] op_sel_hi:[1,0]
	v_pk_mul_f32 v[68:69], v[68:69], v[194:195] op_sel_hi:[1,0]
	v_pk_mul_f32 v[66:67], v[66:67], v[194:195] op_sel_hi:[1,0]
	v_pk_mul_f32 v[60:61], v[60:61], v[194:195] op_sel_hi:[1,0]
	v_pk_mul_f32 v[58:59], v[58:59], v[194:195] op_sel_hi:[1,0]
	v_pk_mul_f32 v[56:57], v[56:57], v[194:195] op_sel_hi:[1,0]
	v_pk_mul_f32 v[54:55], v[54:55], v[194:195] op_sel_hi:[1,0]
	v_pk_mul_f32 v[48:49], v[48:49], v[194:195] op_sel_hi:[1,0]
	v_pk_mul_f32 v[46:47], v[46:47], v[194:195] op_sel_hi:[1,0]
	v_pk_mul_f32 v[40:41], v[40:41], v[194:195] op_sel_hi:[1,0]
	v_pk_mul_f32 v[38:39], v[38:39], v[194:195] op_sel_hi:[1,0]
	v_pk_mul_f32 v[36:37], v[36:37], v[194:195] op_sel_hi:[1,0]
	v_pk_mul_f32 v[34:35], v[34:35], v[194:195] op_sel_hi:[1,0]
	v_pk_mul_f32 v[28:29], v[28:29], v[194:195] op_sel_hi:[1,0]
	v_pk_mul_f32 v[26:27], v[26:27], v[194:195] op_sel_hi:[1,0]
.Lmy_upd:
	v_add_f32_e32 v200, v200, v199
	v_add_f32_e32 v198, v198, v201
	v_sub_f32_e32 v18, 0, v200
	v_sub_f32_e32 v19, 0, v200
	v_sub_f32_e32 v20, 0, v200
	v_sub_f32_e32 v21, 0, v200
	v_sub_f32_e32 v22, 0, v198
	v_sub_f32_e32 v23, 0, v198
	v_sub_f32_e32 v24, 0, v198
	v_sub_f32_e32 v25, 0, v198
	v_sub_f32_e32 v154, v154, v199
	v_sub_f32_e32 v155, v155, v199
	v_sub_f32_e32 v156, v156, v199
	v_sub_f32_e32 v157, v157, v199
	v_sub_f32_e32 v158, v158, v199
	v_sub_f32_e32 v159, v159, v199
	v_sub_f32_e32 v160, v160, v199
	v_sub_f32_e32 v161, v161, v199
	v_sub_f32_e32 v162, v162, v199
	v_sub_f32_e32 v163, v163, v199
	v_sub_f32_e32 v164, v164, v199
	v_sub_f32_e32 v165, v165, v199
	v_sub_f32_e32 v166, v166, v199
	v_sub_f32_e32 v167, v167, v199
	v_sub_f32_e32 v168, v168, v199
	v_sub_f32_e32 v169, v169, v199
	v_sub_f32_e32 v138, v138, v201
	v_sub_f32_e32 v139, v139, v201
	v_sub_f32_e32 v140, v140, v201
	v_sub_f32_e32 v141, v141, v201
	v_sub_f32_e32 v142, v142, v201
	v_sub_f32_e32 v143, v143, v201
	v_sub_f32_e32 v144, v144, v201
	v_sub_f32_e32 v145, v145, v201
	v_sub_f32_e32 v146, v146, v201
	v_sub_f32_e32 v147, v147, v201
	v_sub_f32_e32 v148, v148, v201
	v_sub_f32_e32 v149, v149, v201
	v_sub_f32_e32 v150, v150, v201
	v_sub_f32_e32 v151, v151, v201
	v_sub_f32_e32 v152, v152, v201
	v_sub_f32_e32 v153, v153, v201
	s_branch .LBB0_52
.Lmy_first:
	v_mov_b32_e32 v199, v194
	v_mov_b32_e32 v201, v195
	s_branch .Lmy_upd
.LBB0_52:
	v_exp_f32_e32 v194, v167
	v_exp_f32_e32 v168, v168
	v_exp_f32_e32 v204, v163
	v_exp_f32_e32 v208, v159
	v_exp_f32_e32 v166, v166
	v_exp_f32_e32 v202, v169
	v_exp_f32_e32 v164, v164
	v_exp_f32_e32 v160, v160
	v_exp_f32_e32 v212, v155
	v_exp_f32_e32 v167, v150
	v_exp_f32_e32 v216, v157
	v_exp_f32_e32 v195, v151
	v_exp_f32_e32 v169, v152
	v_exp_f32_e32 v203, v153
	v_exp_f32_e32 v162, v162
	v_exp_f32_e32 v206, v165
	v_exp_f32_e32 v163, v146
	v_pk_add_f32 v[150:151], v[166:167], 0 op_sel_hi:[1,0]
	v_exp_f32_e32 v205, v147
	v_pk_add_f32 v[150:151], v[194:195], v[150:151]
	v_exp_f32_e32 v165, v148
	v_pk_add_f32 v[150:151], v[168:169], v[150:151]
	v_exp_f32_e32 v207, v149
	v_pk_add_f32 v[150:151], v[202:203], v[150:151]
	v_exp_f32_e32 v158, v158
	v_exp_f32_e32 v210, v161
	v_pk_add_f32 v[150:151], v[162:163], v[150:151]
	v_exp_f32_e32 v159, v142
	v_pk_add_f32 v[150:151], v[204:205], v[150:151]
	v_exp_f32_e32 v209, v143
	v_exp_f32_e32 v156, v156
	v_pk_add_f32 v[150:151], v[164:165], v[150:151]
	v_exp_f32_e32 v161, v144
	v_exp_f32_e32 v155, v138
	v_pk_add_f32 v[150:151], v[206:207], v[150:151]
	v_exp_f32_e32 v211, v145
	v_exp_f32_e32 v213, v139
	v_exp_f32_e32 v154, v154
	v_exp_f32_e32 v157, v140
	v_pk_add_f32 v[138:139], v[158:159], v[150:151]
	v_pk_add_f32 v[138:139], v[208:209], v[138:139]
	v_exp_f32_e32 v217, v141
	v_pk_add_f32 v[138:139], v[160:161], v[138:139]
	v_cvt_pk_bf16_f32 v146, v166, v194
	v_pk_add_f32 v[138:139], v[210:211], v[138:139]
	v_cvt_pk_bf16_f32 v147, v168, v202
	v_pk_add_f32 v[138:139], v[154:155], v[138:139]
	v_cvt_pk_bf16_f32 v148, v162, v204
	v_pk_add_f32 v[138:139], v[212:213], v[138:139]
	v_cvt_pk_bf16_f32 v149, v164, v206
	v_pk_add_f32 v[138:139], v[156:157], v[138:139]
	v_cvt_pk_bf16_f32 v140, v154, v212
	v_pk_add_f32 v[142:143], v[216:217], v[138:139]
	v_cvt_pk_bf16_f32 v138, v158, v208
	v_cvt_pk_bf16_f32 v139, v160, v210
	v_cvt_pk_bf16_f32 v141, v156, v216
	v_pk_add_f32 v[178:179], v[142:143], v[178:179]
	v_cvt_pk_bf16_f32 v142, v167, v195
	v_cvt_pk_bf16_f32 v143, v169, v203
	v_cvt_pk_bf16_f32 v144, v163, v205
	v_cvt_pk_bf16_f32 v145, v165, v207
	v_cvt_pk_bf16_f32 v150, v159, v209
	v_cvt_pk_bf16_f32 v151, v161, v211
	v_cvt_pk_bf16_f32 v152, v155, v213
	v_cvt_pk_bf16_f32 v153, v157, v217
	ds_read_b128 v[154:157], v0 offset:16384
	ds_read_b128 v[158:161], v0 offset:17408
	ds_read_b128 v[162:165], v0 offset:18432
	ds_read_b128 v[166:169], v0 offset:19456
	ds_read_b128 v[202:205], v0 offset:20480
	ds_read_b128 v[206:209], v0 offset:21504
	ds_read_b128 v[210:213], v0 offset:22528
	ds_read_b128 v[216:219], v0 offset:23552
	s_waitcnt lgkmcnt(8)
	v_mfma_f32_16x16x32_bf16 v[90:93], v[134:137], v[146:149], v[90:93]
	v_mfma_f32_16x16x32_bf16 v[70:73], v[134:137], v[142:145], v[70:73]
	v_mfma_f32_16x16x32_bf16 v[102:105], v[126:129], v[146:149], v[102:105]
	v_mfma_f32_16x16x32_bf16 v[66:69], v[126:129], v[142:145], v[66:69]
	v_mfma_f32_16x16x32_bf16 v[98:101], v[118:121], v[146:149], v[98:101]
	v_mfma_f32_16x16x32_bf16 v[58:61], v[118:121], v[142:145], v[58:61]
	v_mfma_f32_16x16x32_bf16 v[94:97], v[110:113], v[146:149], v[94:97]
	v_mfma_f32_16x16x32_bf16 v[54:57], v[110:113], v[142:145], v[54:57]
	s_waitcnt lgkmcnt(7)
	v_mfma_f32_16x16x32_bf16 v[86:89], v[154:157], v[146:149], v[86:89]
	v_mfma_f32_16x16x32_bf16 v[46:49], v[154:157], v[142:145], v[46:49]
	s_waitcnt lgkmcnt(5)
	v_mfma_f32_16x16x32_bf16 v[82:85], v[162:165], v[146:149], v[82:85]
	v_mfma_f32_16x16x32_bf16 v[38:41], v[162:165], v[142:145], v[38:41]
	s_waitcnt lgkmcnt(3)
	v_mfma_f32_16x16x32_bf16 v[78:81], v[202:205], v[146:149], v[78:81]
	v_mfma_f32_16x16x32_bf16 v[34:37], v[202:205], v[142:145], v[34:37]
	s_waitcnt lgkmcnt(1)
	v_mfma_f32_16x16x32_bf16 v[74:77], v[210:213], v[146:149], v[74:77]
	v_mfma_f32_16x16x32_bf16 v[26:29], v[210:213], v[142:145], v[26:29]
	v_mfma_f32_16x16x32_bf16 v[90:93], v[130:133], v[138:141], v[90:93]
	v_mfma_f32_16x16x32_bf16 v[70:73], v[130:133], v[150:153], v[70:73]
	v_mfma_f32_16x16x32_bf16 v[102:105], v[122:125], v[138:141], v[102:105]
	v_mfma_f32_16x16x32_bf16 v[66:69], v[122:125], v[150:153], v[66:69]
	v_mfma_f32_16x16x32_bf16 v[98:101], v[114:117], v[138:141], v[98:101]
	v_mfma_f32_16x16x32_bf16 v[58:61], v[114:117], v[150:153], v[58:61]
	v_mfma_f32_16x16x32_bf16 v[94:97], v[106:109], v[138:141], v[94:97]
	v_mfma_f32_16x16x32_bf16 v[54:57], v[106:109], v[150:153], v[54:57]
	v_mfma_f32_16x16x32_bf16 v[86:89], v[158:161], v[138:141], v[86:89]
	v_mfma_f32_16x16x32_bf16 v[46:49], v[158:161], v[150:153], v[46:49]
	v_mfma_f32_16x16x32_bf16 v[82:85], v[166:169], v[138:141], v[82:85]
	v_mfma_f32_16x16x32_bf16 v[38:41], v[166:169], v[150:153], v[38:41]
	v_mfma_f32_16x16x32_bf16 v[78:81], v[206:209], v[138:141], v[78:81]
	v_mfma_f32_16x16x32_bf16 v[34:37], v[206:209], v[150:153], v[34:37]
	s_waitcnt lgkmcnt(0)
	v_mfma_f32_16x16x32_bf16 v[74:77], v[216:219], v[138:141], v[74:77]
	v_mfma_f32_16x16x32_bf16 v[26:29], v[216:219], v[150:153], v[26:29]
	s_xor_b32 s53, s53, 1
	s_add_i32 s49, s49, 64
	s_add_i32 s54, s54, 1
	s_add_u32 s98, s98, 0x4000
	s_addc_u32 s99, s99, 0
	s_add_u32 s2, s2, 0x2000
	s_addc_u32 s3, s3, 0
	s_cmp_lg_u32 s1, s54
	s_cbranch_scc0 .LBB0_42
	s_branch .LBB0_46

.LBB0_702:
	s_or_b64 exec, exec, s[14:15]
	s_waitcnt lgkmcnt(0)
	s_add_u32 s69, s86, s46
	s_addc_u32 s79, s87, s47
	s_movk_i32 s14, 0x104
	s_cmp_gt_i32 s53, -1
	s_mov_b32 s94, s53
	v_mul_lo_u32 v0, v37, s14
	s_cselect_b64 s[46:47], -1, 0
	s_lshl_b64 s[14:15], s[94:95], 3
	v_readlane_b32 s44, v253, 0
	v_readlane_b32 s45, v253, 1
	s_add_u32 s70, s44, s14
	s_addc_u32 s71, s45, s15
	s_ashr_i32 s55, s54, 31
	s_ashr_i32 s49, s48, 31
	v_lshl_add_u32 v0, v36, 2, v0
	s_cmp_eq_u32 s52, 0
	s_waitcnt vmcnt(0)
	ds_write2_b32 v0, v6, v7 offset1:1
	ds_write2_b32 v0, v8, v9 offset0:2 offset1:3
	v_add_u32_e32 v6, 0x1040, v0
	s_cselect_b64 s[44:45], -1, 0
	s_add_i32 s14, s68, 0xfffff540
	ds_write2_b32 v6, v2, v3 offset1:1
	v_add_u32_e32 v2, 0x1048, v0
	s_lshr_b32 s14, s14, 6
	ds_write2_b32 v2, v4, v5 offset1:1
	v_add_u32_e32 v2, 0x2080, v0
	s_cmp_gt_i32 s78, 42
	ds_write2_b32 v2, v14, v15 offset1:1
	v_add_u32_e32 v2, 0x2088, v0
	s_cselect_b32 s14, s14, s78
	ds_write2_b32 v2, v16, v17 offset1:1
	v_add_u32_e32 v2, 0x30c0, v0
	v_add_u32_e32 v0, 0x30c8, v0
	s_cselect_b32 s15, 64, 0
	s_lshl_b32 s14, s14, 7
	ds_write2_b32 v0, v12, v13 offset1:1
	v_lshlrev_b32_e32 v0, 3, v35
	s_or_b32 s14, s14, s15
	s_lshl_b64 s[52:53], s[48:49], 1
	v_ashrrev_i32_e32 v13, 3, v35
	v_and_b32_e32 v12, 56, v0
	s_add_u32 s52, s69, s52
	s_addc_u32 s53, s79, s53
	v_lshlrev_b32_e32 v0, 1, v12
	v_add_u32_e32 v14, s68, v13
	v_cndmask_b32_e64 v4, 0, 1, s[46:47]
	ds_write2_b32 v2, v10, v11 offset1:1
	v_lshl_add_u64 v[2:3], s[52:53], 0, v[0:1]
	v_cmp_gt_i32_e32 vcc, s13, v14
	v_mul_u32_u24_e32 v0, 0x104, v12
	v_cmp_ne_u32_e64 s[46:47], 1, v4
	s_waitcnt lgkmcnt(0)
	s_barrier
	s_and_saveexec_b64 s[52:53], vcc
	s_cbranch_execz .LBB0_706
	v_lshl_add_u32 v8, v13, 2, v0
	v_add_u32_e32 v10, 0x400, v8
	ds_read2_b32 v[4:5], v8 offset1:65
	ds_read2_b32 v[6:7], v8 offset0:130 offset1:195
	ds_read2_b32 v[8:9], v10 offset0:4 offset1:69
	ds_read2_b32 v[10:11], v10 offset0:134 offset1:199
	s_and_b64 vcc, exec, s[46:47]
	s_cbranch_vccnz .LBB0_705
	s_load_dwordx2 s[78:79], s[70:71], 0x0
	s_lshl_b64 s[80:81], s[54:55], 2
	v_lshlrev_b32_e32 v15, 2, v12
	s_waitcnt lgkmcnt(0)
	s_add_u32 s15, s78, s80
	s_addc_u32 s69, s79, s81
	v_readlane_b32 s78, v254, 44
	v_readlane_b32 s79, v254, 45
	s_add_u32 s15, s15, s78
	s_addc_u32 s69, s69, s79
	s_lshl_b64 s[78:79], s[48:49], 2
	s_add_u32 s78, s15, s78
	s_addc_u32 s79, s69, s79
	global_load_dwordx4 v[36:39], v15, s[78:79]
	global_load_dwordx4 v[40:43], v15, s[78:79] offset:16
	s_movk_i32 s80, 0x3000
	s_movk_i32 s81, 0x2000
	s_waitcnt vmcnt(1)
	v_pk_mul_f32 v[4:5], v[4:5], v[36:37]
	v_pk_mul_f32 v[6:7], v[6:7], v[38:39]
	s_waitcnt vmcnt(0)
	v_pk_mul_f32 v[8:9], v[8:9], v[40:41]
	v_pk_mul_f32 v[10:11], v[10:11], v[42:43]
	s_cmp_eq_u32 s94, 9
	s_cbranch_scc0 .Lmy_nosc_b
	s_cmpk_lt_u32 s68, 0x400
	s_cbranch_scc0 .Lmy_nosc_b
	v_mul_f32_e32 v4, 0x3e38aa3b, v4
	v_mul_f32_e32 v5, 0x3e38aa3b, v5
	v_mul_f32_e32 v6, 0x3e38aa3b, v6
	v_mul_f32_e32 v7, 0x3e38aa3b, v7
	v_mul_f32_e32 v8, 0x3e38aa3b, v8
	v_mul_f32_e32 v9, 0x3e38aa3b, v9
	v_mul_f32_e32 v10, 0x3e38aa3b, v10
	v_mul_f32_e32 v11, 0x3e38aa3b, v11
.Lmy_nosc_b:
.LBB0_705:
	v_add_u32_e32 v15, s14, v13
	v_cndmask_b32_e64 v14, v15, v14, s[44:45]
	s_waitcnt lgkmcnt(3)
	v_cvt_pk_bf16_f32 v4, v4, v5
	s_waitcnt lgkmcnt(2)
	v_cvt_pk_bf16_f32 v5, v6, v7
	s_waitcnt lgkmcnt(1)
	v_cvt_pk_bf16_f32 v6, v8, v9
	v_mad_i64_i32 v[8:9], s[78:79], v14, s12, 0
	s_waitcnt lgkmcnt(0)
	v_cvt_pk_bf16_f32 v7, v10, v11
	v_lshl_add_u64 v[8:9], v[8:9], 1, v[2:3]
	global_store_dwordx4 v[8:9], v[4:7], off
.LBB0_706:
	s_or_b64 exec, exec, s[52:53]
	v_add_u32_e32 v14, 32, v13
	v_add_u32_e32 v15, s68, v14
	v_cmp_gt_i32_e32 vcc, s13, v15
	s_and_saveexec_b64 s[52:53], vcc
	s_cbranch_execz .LBB0_659
	v_lshl_add_u32 v0, v13, 2, v0
	ds_read2_b32 v[4:5], v0 offset0:32 offset1:97
	ds_read2_b32 v[6:7], v0 offset0:162 offset1:227
	v_add_u32_e32 v0, 0x400, v0
	ds_read2_b32 v[8:9], v0 offset0:36 offset1:101
	ds_read2_b32 v[10:11], v0 offset0:166 offset1:231
	s_and_b64 vcc, exec, s[46:47]
	s_cbranch_vccnz .LBB0_658
	s_load_dwordx2 s[46:47], s[70:71], 0x0
	s_lshl_b64 s[54:55], s[54:55], 2
	v_lshlrev_b32_e32 v0, 2, v12
	s_waitcnt lgkmcnt(0)
	s_add_u32 s13, s46, s54
	s_addc_u32 s15, s47, s55
	v_readlane_b32 s46, v254, 44
	v_readlane_b32 s47, v254, 45
	s_add_u32 s13, s13, s46
	s_addc_u32 s15, s15, s47
	s_lshl_b64 s[46:47], s[48:49], 2
	s_add_u32 s46, s13, s46
	s_addc_u32 s47, s15, s47
	global_load_dwordx4 v[36:39], v0, s[46:47]
	global_load_dwordx4 v[40:43], v0, s[46:47] offset:16
	s_waitcnt vmcnt(1)
	v_pk_mul_f32 v[4:5], v[4:5], v[36:37]
	v_pk_mul_f32 v[6:7], v[6:7], v[38:39]
	s_waitcnt vmcnt(0)
	v_pk_mul_f32 v[8:9], v[8:9], v[40:41]
	v_pk_mul_f32 v[10:11], v[10:11], v[42:43]
	s_cmp_eq_u32 s94, 9
	s_cbranch_scc0 .Lmy_nosc_a
	s_cmpk_lt_u32 s68, 0x400
	s_cbranch_scc0 .Lmy_nosc_a
	v_mul_f32_e32 v4, 0x3e38aa3b, v4
	v_mul_f32_e32 v5, 0x3e38aa3b, v5
	v_mul_f32_e32 v6, 0x3e38aa3b, v6
	v_mul_f32_e32 v7, 0x3e38aa3b, v7
	v_mul_f32_e32 v8, 0x3e38aa3b, v8
	v_mul_f32_e32 v9, 0x3e38aa3b, v9
	v_mul_f32_e32 v10, 0x3e38aa3b, v10
	v_mul_f32_e32 v11, 0x3e38aa3b, v11
.Lmy_nosc_a:
	s_branch .LBB0_658
